# fc2 epilogue fused with final RMSNorm (per-row-panel counters, f32 out from accumulators), final-norm phase + its grid barrier removed; wave halves re-staggered per tile
# speedup vs baseline: 1.0184x; 1.0137x over previous
.LBB0_23:
	v_readlane_b32 s0, v255, 24
	s_nop 0
	v_writelane_b32 v255, s54, 26
	s_add_i32 s0, s0, 1
	v_readlane_b32 s94, v255, 22
	v_readlane_b32 s24, v255, 16
	v_readlane_b32 s50, v255, 18
	v_readlane_b32 s54, v255, 20
	s_min_i32 s1, s67, 7
	s_cmp_ge_i32 s0, s1
	v_readlane_b32 s95, v255, 23
	v_readlane_b32 s25, v255, 17
	v_readlane_b32 s51, v255, 19
	v_readlane_b32 s55, v255, 21
	s_cbranch_scc1 .LBB0_447

.LBB0_92:
	s_or_b64 exec, exec, s[28:29]
	s_and_b64 vcc, exec, s[40:41]
	s_mov_b32 s34, s0
	s_mov_b32 s2, s42
	s_mov_b64 s[28:29], s[46:47]
	s_mov_b64 s[48:49], s[44:45]
	s_cbranch_vccnz .LBB0_117
	s_cmpk_gt_u32 s92, 0xff
	s_cbranch_scc0 .Lf2e_noy
	s_barrier
.Lf2e_noy:
.LBB0_93:
	s_add_i32 s6, s6, 1
	s_mul_i32 s1, s6, s3
	s_mul_hi_u32 s20, s6, s59
	s_add_i32 s20, s20, s1
	s_mul_i32 s1, s6, s59
	s_add_u32 s44, s1, s96
	s_addc_u32 s45, s20, s97
	s_waitcnt lgkmcnt(0)
	v_mov_b64_e32 v[0:1], 0x1ff
	v_cmp_gt_i64_e64 s[40:41], s[44:45], v[0:1]
	s_and_b64 vcc, exec, s[40:41]
	s_cbranch_vccnz .LBB0_99
	s_ashr_i32 s0, s44, 31
	s_lshr_b32 s0, s0, 29
	s_add_i32 s20, s44, s0
	s_and_b32 s0, s20, -8
	s_sub_i32 s21, s44, s0
	s_cmp_gt_i32 s21, -1
	s_mov_b64 s[0:1], -1
	s_cbranch_scc0 .LBB0_96
	s_lshl_b32 s24, s21, 6
	s_mov_b64 s[0:1], 0

.LBB0_100:
	s_add_u32 s21, s48, 0xfff00080
	s_addc_u32 s28, s49, -1
	s_add_i32 s60, 0, 0x10000
	v_add_u32_e32 v124, s60, v175
	ds_read_b128 v[112:115], v124
	ds_read_b128 v[116:119], v124 offset:1024
	ds_read_b128 v[120:123], v124 offset:2048
	ds_read_b128 v[124:127], v124 offset:3072
	s_cmp_eq_u32 s20, 60
	s_cselect_b32 s51, s43, s28
	s_cselect_b32 s50, s24, s21
	s_cselect_b32 s29, s1, vcc_hi
	s_cselect_b32 s28, s25, vcc_lo
	s_add_i32 m0, s55, 0xc000
	ds_read_b128 v[128:131], v199
	ds_read_b128 v[132:135], v199 offset:1024
	ds_read_b128 v[162:165], v199 offset:2048
	ds_read_b128 v[166:169], v199 offset:3072
	ds_read_b128 v[170:173], v199 offset:4096
	ds_read_b128 v[200:203], v199 offset:5120
	ds_read_b128 v[204:207], v199 offset:6144
	ds_read_b128 v[208:211], v199 offset:7168
	global_load_lds_dwordx4 v158, s[48:49]
	s_add_i32 m0, s55, 0xe000
	s_nop 0
	global_load_lds_dwordx4 v160, s[48:49]
	s_waitcnt lgkmcnt(8)
	s_barrier
	s_waitcnt lgkmcnt(0)
	v_mfma_f32_16x16x32_bf16 v[148:151], v[112:115], v[128:131], v[148:151]
	v_mfma_f32_16x16x32_bf16 v[144:147], v[120:123], v[128:131], v[144:147]
	v_mfma_f32_16x16x32_bf16 v[108:111], v[112:115], v[162:165], v[108:111]
	v_mfma_f32_16x16x32_bf16 v[104:107], v[120:123], v[162:165], v[104:107]
	v_mfma_f32_16x16x32_bf16 v[92:95], v[112:115], v[170:173], v[92:95]
	v_mfma_f32_16x16x32_bf16 v[88:91], v[120:123], v[170:173], v[88:91]
	v_mfma_f32_16x16x32_bf16 v[76:79], v[112:115], v[204:207], v[76:79]
	v_mfma_f32_16x16x32_bf16 v[72:75], v[120:123], v[204:207], v[72:75]
	v_mfma_f32_16x16x32_bf16 v[148:151], v[116:119], v[132:135], v[148:151]
	v_mfma_f32_16x16x32_bf16 v[144:147], v[124:127], v[132:135], v[144:147]
	v_mfma_f32_16x16x32_bf16 v[108:111], v[116:119], v[166:169], v[108:111]
	v_mfma_f32_16x16x32_bf16 v[104:107], v[124:127], v[166:169], v[104:107]
	v_mfma_f32_16x16x32_bf16 v[92:95], v[116:119], v[200:203], v[92:95]
	v_mfma_f32_16x16x32_bf16 v[88:91], v[124:127], v[200:203], v[88:91]
	v_mfma_f32_16x16x32_bf16 v[76:79], v[116:119], v[208:211], v[76:79]
	v_mfma_f32_16x16x32_bf16 v[72:75], v[124:127], v[208:211], v[72:75]
	s_barrier
	s_add_i32 s21, 0, 0x14000
	v_add_u32_e32 v184, s21, v175
	s_add_i32 s60, s60, s54
	ds_read_b128 v[212:215], v184
	ds_read_b128 v[216:219], v184 offset:1024
	ds_read_b128 v[232:235], v184 offset:2048
	ds_read_b128 v[236:239], v184 offset:3072
	s_add_u32 s72, s28, s52
	s_addc_u32 s73, s29, s53
	s_mov_b32 m0, s60
	s_nop 0
	global_load_lds_dwordx4 v176, s[28:29]
	s_add_i32 m0, s60, 0x2000
	s_nop 0
	global_load_lds_dwordx4 v152, s[28:29]
	s_barrier
	s_waitcnt lgkmcnt(0)
	v_mfma_f32_16x16x32_bf16 v[140:143], v[212:215], v[128:131], v[140:143]
	v_mfma_f32_16x16x32_bf16 v[100:103], v[212:215], v[162:165], v[100:103]
	v_mfma_f32_16x16x32_bf16 v[96:99], v[232:235], v[162:165], v[96:99]
	v_mfma_f32_16x16x32_bf16 v[84:87], v[212:215], v[170:173], v[84:87]
	v_mfma_f32_16x16x32_bf16 v[80:83], v[232:235], v[170:173], v[80:83]
	v_mfma_f32_16x16x32_bf16 v[68:71], v[212:215], v[204:207], v[68:71]
	v_mfma_f32_16x16x32_bf16 v[64:67], v[232:235], v[204:207], v[64:67]
	v_mfma_f32_16x16x32_bf16 v[140:143], v[216:219], v[132:135], v[140:143]
	v_mfma_f32_16x16x32_bf16 v[128:131], v[232:235], v[128:131], v[136:139]
	v_mfma_f32_16x16x32_bf16 v[100:103], v[216:219], v[166:169], v[100:103]
	v_mfma_f32_16x16x32_bf16 v[96:99], v[236:239], v[166:169], v[96:99]
	v_mfma_f32_16x16x32_bf16 v[84:87], v[216:219], v[200:203], v[84:87]
	v_mfma_f32_16x16x32_bf16 v[80:83], v[236:239], v[200:203], v[80:83]
	v_mfma_f32_16x16x32_bf16 v[68:71], v[216:219], v[208:211], v[68:71]
	v_mfma_f32_16x16x32_bf16 v[64:67], v[236:239], v[208:211], v[64:67]
	v_mfma_f32_16x16x32_bf16 v[128:131], v[236:239], v[132:135], v[128:131]
	s_mov_b32 m0, s55
	s_add_u32 s94, s50, s52
	s_addc_u32 s95, s51, s53
	s_barrier
	ds_read_b128 v[132:135], v199 offset:16384
	ds_read_b128 v[136:139], v199 offset:17408
	ds_read_b128 v[162:165], v199 offset:18432
	ds_read_b128 v[166:169], v199 offset:19456
	ds_read_b128 v[170:173], v199 offset:20480
	ds_read_b128 v[200:203], v199 offset:21504
	ds_read_b128 v[204:207], v199 offset:22528
	ds_read_b128 v[208:211], v199 offset:23552
	global_load_lds_dwordx4 v156, s[50:51]
	s_mov_b32 m0, s56
	s_nop 0
	global_load_lds_dwordx4 v154, s[50:51]
	s_barrier
	s_waitcnt lgkmcnt(0)
	v_mfma_f32_16x16x32_bf16 v[60:63], v[112:115], v[132:135], v[60:63]
	v_mfma_f32_16x16x32_bf16 v[56:59], v[120:123], v[132:135], v[56:59]
	v_mfma_f32_16x16x32_bf16 v[44:47], v[112:115], v[162:165], v[44:47]
	v_mfma_f32_16x16x32_bf16 v[40:43], v[120:123], v[162:165], v[40:43]
	v_mfma_f32_16x16x32_bf16 v[28:31], v[112:115], v[170:173], v[28:31]
	v_mfma_f32_16x16x32_bf16 v[24:27], v[120:123], v[170:173], v[24:27]
	v_mfma_f32_16x16x32_bf16 v[12:15], v[112:115], v[204:207], v[12:15]
	v_mfma_f32_16x16x32_bf16 v[8:11], v[120:123], v[204:207], v[8:11]
	v_mfma_f32_16x16x32_bf16 v[60:63], v[116:119], v[136:139], v[60:63]
	v_mfma_f32_16x16x32_bf16 v[56:59], v[124:127], v[136:139], v[56:59]
	v_mfma_f32_16x16x32_bf16 v[44:47], v[116:119], v[166:169], v[44:47]
	v_mfma_f32_16x16x32_bf16 v[40:43], v[124:127], v[166:169], v[40:43]
	v_mfma_f32_16x16x32_bf16 v[28:31], v[116:119], v[200:203], v[28:31]
	v_mfma_f32_16x16x32_bf16 v[24:27], v[124:127], v[200:203], v[24:27]
	v_mfma_f32_16x16x32_bf16 v[12:15], v[116:119], v[208:211], v[12:15]
	v_mfma_f32_16x16x32_bf16 v[8:11], v[124:127], v[208:211], v[8:11]
	s_barrier
	s_add_u32 s60, s28, 0x100000
	s_addc_u32 s61, s29, 0
	s_add_i32 s21, s21, s54
	s_mov_b32 m0, s21
	s_nop 0
	global_load_lds_dwordx4 v176, s[60:61]
	s_add_i32 m0, s21, 0x2000
	s_nop 0
	global_load_lds_dwordx4 v152, s[60:61]
	s_waitcnt vmcnt(6)
	s_barrier
	v_mfma_f32_16x16x32_bf16 v[52:55], v[212:215], v[132:135], v[52:55]
	v_mfma_f32_16x16x32_bf16 v[48:51], v[232:235], v[132:135], v[48:51]
	v_mfma_f32_16x16x32_bf16 v[36:39], v[212:215], v[162:165], v[36:39]
	v_mfma_f32_16x16x32_bf16 v[32:35], v[232:235], v[162:165], v[32:35]
	v_mfma_f32_16x16x32_bf16 v[20:23], v[212:215], v[170:173], v[20:23]
	v_mfma_f32_16x16x32_bf16 v[16:19], v[232:235], v[170:173], v[16:19]
	v_mfma_f32_16x16x32_bf16 v[4:7], v[212:215], v[204:207], v[4:7]
	v_mfma_f32_16x16x32_bf16 v[0:3], v[232:235], v[204:207], v[0:3]
	v_mfma_f32_16x16x32_bf16 v[52:55], v[216:219], v[136:139], v[52:55]
	v_mfma_f32_16x16x32_bf16 v[48:51], v[236:239], v[136:139], v[48:51]
	v_mfma_f32_16x16x32_bf16 v[36:39], v[216:219], v[166:169], v[36:39]
	v_mfma_f32_16x16x32_bf16 v[32:35], v[236:239], v[166:169], v[32:35]
	v_mfma_f32_16x16x32_bf16 v[20:23], v[216:219], v[200:203], v[20:23]
	v_mfma_f32_16x16x32_bf16 v[16:19], v[236:239], v[200:203], v[16:19]
	v_mfma_f32_16x16x32_bf16 v[4:7], v[216:219], v[208:211], v[4:7]
	v_mfma_f32_16x16x32_bf16 v[0:3], v[236:239], v[208:211], v[0:3]
	s_add_i32 s21, 0, 0x18000
	v_add_u32_e32 v124, s21, v175
	s_barrier
	ds_read_b128 v[112:115], v124
	ds_read_b128 v[116:119], v124 offset:1024
	ds_read_b128 v[120:123], v124 offset:2048
	ds_read_b128 v[124:127], v124 offset:3072
	s_add_u32 s50, s50, 0x100000
	s_addc_u32 s51, s51, 0
	s_mov_b32 m0, s57
	ds_read_b128 v[132:135], v199 offset:32768
	ds_read_b128 v[136:139], v199 offset:33792
	ds_read_b128 v[162:165], v199 offset:34816
	ds_read_b128 v[166:169], v199 offset:35840
	ds_read_b128 v[170:173], v199 offset:36864
	ds_read_b128 v[200:203], v199 offset:37888
	ds_read_b128 v[204:207], v199 offset:38912
	ds_read_b128 v[208:211], v199 offset:39936
	global_load_lds_dwordx4 v156, s[50:51]
	s_mov_b32 m0, s58
	s_nop 0
	global_load_lds_dwordx4 v154, s[50:51]
	s_waitcnt lgkmcnt(8)
	s_barrier
	s_waitcnt lgkmcnt(0)
	v_mfma_f32_16x16x32_bf16 v[148:151], v[112:115], v[132:135], v[148:151]
	v_mfma_f32_16x16x32_bf16 v[144:147], v[120:123], v[132:135], v[144:147]
	v_mfma_f32_16x16x32_bf16 v[108:111], v[112:115], v[162:165], v[108:111]
	v_mfma_f32_16x16x32_bf16 v[104:107], v[120:123], v[162:165], v[104:107]
	v_mfma_f32_16x16x32_bf16 v[92:95], v[112:115], v[170:173], v[92:95]
	v_mfma_f32_16x16x32_bf16 v[88:91], v[120:123], v[170:173], v[88:91]
	v_mfma_f32_16x16x32_bf16 v[76:79], v[112:115], v[204:207], v[76:79]
	v_mfma_f32_16x16x32_bf16 v[72:75], v[120:123], v[204:207], v[72:75]
	v_mfma_f32_16x16x32_bf16 v[148:151], v[116:119], v[136:139], v[148:151]
	v_mfma_f32_16x16x32_bf16 v[144:147], v[124:127], v[136:139], v[144:147]
	v_mfma_f32_16x16x32_bf16 v[108:111], v[116:119], v[166:169], v[108:111]
	v_mfma_f32_16x16x32_bf16 v[104:107], v[124:127], v[166:169], v[104:107]
	v_mfma_f32_16x16x32_bf16 v[92:95], v[116:119], v[200:203], v[92:95]
	v_mfma_f32_16x16x32_bf16 v[88:91], v[124:127], v[200:203], v[88:91]
	v_mfma_f32_16x16x32_bf16 v[76:79], v[116:119], v[208:211], v[76:79]
	v_mfma_f32_16x16x32_bf16 v[72:75], v[124:127], v[208:211], v[72:75]
	s_barrier
	s_add_i32 s50, 0, 0x1c000
	s_add_i32 s21, s21, s54
	v_add_u32_e32 v231, s50, v175
	s_mov_b32 m0, s21
	ds_read_b128 v[212:215], v231
	ds_read_b128 v[216:219], v231 offset:1024
	ds_read_b128 v[232:235], v231 offset:2048
	ds_read_b128 v[236:239], v231 offset:3072
	global_load_lds_dwordx4 v176, s[72:73]
	s_add_i32 m0, s21, 0x2000
	s_nop 0
	global_load_lds_dwordx4 v152, s[72:73]
	s_barrier
	s_waitcnt lgkmcnt(0)
	v_mfma_f32_16x16x32_bf16 v[140:143], v[212:215], v[132:135], v[140:143]
	v_mfma_f32_16x16x32_bf16 v[128:131], v[232:235], v[132:135], v[128:131]
	v_mfma_f32_16x16x32_bf16 v[100:103], v[212:215], v[162:165], v[100:103]
	v_mfma_f32_16x16x32_bf16 v[96:99], v[232:235], v[162:165], v[96:99]
	v_mfma_f32_16x16x32_bf16 v[84:87], v[212:215], v[170:173], v[84:87]
	v_mfma_f32_16x16x32_bf16 v[80:83], v[232:235], v[170:173], v[80:83]
	v_mfma_f32_16x16x32_bf16 v[68:71], v[212:215], v[204:207], v[68:71]
	v_mfma_f32_16x16x32_bf16 v[64:67], v[232:235], v[204:207], v[64:67]
	v_mfma_f32_16x16x32_bf16 v[140:143], v[216:219], v[136:139], v[140:143]
	v_mfma_f32_16x16x32_bf16 v[136:139], v[236:239], v[136:139], v[128:131]
	v_mfma_f32_16x16x32_bf16 v[100:103], v[216:219], v[166:169], v[100:103]
	v_mfma_f32_16x16x32_bf16 v[96:99], v[236:239], v[166:169], v[96:99]
	v_mfma_f32_16x16x32_bf16 v[84:87], v[216:219], v[200:203], v[84:87]
	v_mfma_f32_16x16x32_bf16 v[80:83], v[236:239], v[200:203], v[80:83]
	v_mfma_f32_16x16x32_bf16 v[68:71], v[216:219], v[208:211], v[68:71]
	v_mfma_f32_16x16x32_bf16 v[64:67], v[236:239], v[208:211], v[64:67]
	s_mov_b32 m0, s7
	s_barrier
	ds_read_b128 v[128:131], v199 offset:49152
	ds_read_b128 v[132:135], v199 offset:50176
	ds_read_b128 v[162:165], v199 offset:51200
	ds_read_b128 v[166:169], v199 offset:52224
	ds_read_b128 v[170:173], v199 offset:53248
	ds_read_b128 v[200:203], v199 offset:54272
	ds_read_b128 v[204:207], v199 offset:55296
	ds_read_b128 v[208:211], v199 offset:56320
	global_load_lds_dwordx4 v156, s[94:95]
	s_mov_b32 m0, s15
	s_nop 0
	global_load_lds_dwordx4 v154, s[94:95]
	s_barrier
	s_waitcnt lgkmcnt(0)
	v_mfma_f32_16x16x32_bf16 v[60:63], v[112:115], v[128:131], v[60:63]
	v_mfma_f32_16x16x32_bf16 v[56:59], v[120:123], v[128:131], v[56:59]
	v_mfma_f32_16x16x32_bf16 v[44:47], v[112:115], v[162:165], v[44:47]
	v_mfma_f32_16x16x32_bf16 v[40:43], v[120:123], v[162:165], v[40:43]
	v_mfma_f32_16x16x32_bf16 v[28:31], v[112:115], v[170:173], v[28:31]
	v_mfma_f32_16x16x32_bf16 v[24:27], v[120:123], v[170:173], v[24:27]
	v_mfma_f32_16x16x32_bf16 v[12:15], v[112:115], v[204:207], v[12:15]
	v_mfma_f32_16x16x32_bf16 v[8:11], v[120:123], v[204:207], v[8:11]
	v_mfma_f32_16x16x32_bf16 v[60:63], v[116:119], v[132:135], v[60:63]
	v_mfma_f32_16x16x32_bf16 v[56:59], v[124:127], v[132:135], v[56:59]
	v_mfma_f32_16x16x32_bf16 v[44:47], v[116:119], v[166:169], v[44:47]
	v_mfma_f32_16x16x32_bf16 v[40:43], v[124:127], v[166:169], v[40:43]
	v_mfma_f32_16x16x32_bf16 v[28:31], v[116:119], v[200:203], v[28:31]
	v_mfma_f32_16x16x32_bf16 v[24:27], v[124:127], v[200:203], v[24:27]
	v_mfma_f32_16x16x32_bf16 v[12:15], v[116:119], v[208:211], v[12:15]
	v_mfma_f32_16x16x32_bf16 v[8:11], v[124:127], v[208:211], v[8:11]
	s_barrier
	s_add_u32 s28, s28, 0x100080
	s_addc_u32 s29, s29, 0
	s_add_i32 s21, s50, s54
	s_mov_b32 m0, s21
	s_nop 0
	global_load_lds_dwordx4 v176, s[28:29]
	s_add_i32 m0, s21, 0x2000
	s_nop 0
	global_load_lds_dwordx4 v152, s[28:29]
	s_waitcnt vmcnt(6)
	s_barrier
	v_mfma_f32_16x16x32_bf16 v[52:55], v[212:215], v[128:131], v[52:55]
	v_mfma_f32_16x16x32_bf16 v[48:51], v[232:235], v[128:131], v[48:51]
	v_mfma_f32_16x16x32_bf16 v[36:39], v[212:215], v[162:165], v[36:39]
	v_mfma_f32_16x16x32_bf16 v[32:35], v[232:235], v[162:165], v[32:35]
	v_mfma_f32_16x16x32_bf16 v[20:23], v[212:215], v[170:173], v[20:23]
	v_mfma_f32_16x16x32_bf16 v[16:19], v[232:235], v[170:173], v[16:19]
	v_mfma_f32_16x16x32_bf16 v[4:7], v[212:215], v[204:207], v[4:7]
	v_mfma_f32_16x16x32_bf16 v[0:3], v[232:235], v[204:207], v[0:3]
	v_mfma_f32_16x16x32_bf16 v[52:55], v[216:219], v[132:135], v[52:55]
	v_mfma_f32_16x16x32_bf16 v[48:51], v[236:239], v[132:135], v[48:51]
	v_mfma_f32_16x16x32_bf16 v[36:39], v[216:219], v[166:169], v[36:39]
	v_mfma_f32_16x16x32_bf16 v[32:35], v[236:239], v[166:169], v[32:35]
	v_mfma_f32_16x16x32_bf16 v[20:23], v[216:219], v[200:203], v[20:23]
	v_mfma_f32_16x16x32_bf16 v[16:19], v[236:239], v[200:203], v[16:19]
	v_mfma_f32_16x16x32_bf16 v[4:7], v[216:219], v[208:211], v[4:7]
	v_mfma_f32_16x16x32_bf16 v[0:3], v[236:239], v[208:211], v[0:3]
	s_add_i32 s20, s20, 2
	s_add_u32 s48, s48, 0x100
	s_addc_u32 s49, s49, 0
	s_add_u32 vcc_lo, vcc_lo, 0x100
	s_addc_u32 vcc_hi, vcc_hi, 0
	s_cmp_gt_u32 s20, 61
	s_barrier
	s_cbranch_scc0 .LBB0_100
	v_readlane_b32 s48, v252, 4
	v_readlane_b32 s49, v252, 5
	v_readlane_b32 s60, v252, 6
	v_readlane_b32 s61, v252, 7
	v_lshl_or_b32 v162, s34, 8, v198
	v_lshl_add_u32 v166, s2, 8, v174
	v_lshlrev_b32_e32 v163, 11, v166
	v_lshl_add_u32 v163, v162, 1, v163
	global_load_dwordx4 v[200:203], v163, s[68:69]
	global_load_dwordx4 v[204:207], v163, s[68:69] offset:256
	s_add_u32 s20, s68, 0x8000
	s_addc_u32 s21, s69, 0
	global_load_dwordx4 v[208:211], v163, s[20:21]
	global_load_dwordx4 v[212:215], v163, s[20:21] offset:256
	s_add_u32 s20, s68, 0x10000
	s_addc_u32 s21, s69, 0
	global_load_dwordx4 v[216:219], v163, s[20:21]
	global_load_dwordx4 v[232:235], v163, s[20:21] offset:256
	s_add_u32 s20, s68, 0x18000
	s_addc_u32 s21, s69, 0
	global_load_dwordx4 v[236:239], v163, s[20:21]
	global_load_dwordx4 v[240:243], v163, s[20:21] offset:256
	s_add_u32 s20, s68, 0x40000
	s_addc_u32 s21, s69, 0
	global_load_dwordx4 v[244:247], v163, s[20:21]
	global_load_dwordx4 v[248:251], v163, s[20:21] offset:256
	s_add_u32 s20, s68, 0x48000
	s_addc_u32 s21, s69, 0
	global_load_dwordx4 v[112:115], v163, s[20:21]
	global_load_dwordx4 v[116:119], v163, s[20:21] offset:256
	s_add_u32 s20, s68, 0x50000
	s_addc_u32 s21, s69, 0
	global_load_dwordx4 v[120:123], v163, s[20:21]
	global_load_dwordx4 v[124:127], v163, s[20:21] offset:256
	s_add_u32 s20, s68, 0x58000
	s_addc_u32 s21, s69, 0
	global_load_dwordx4 v[128:131], v163, s[20:21]
	global_load_dwordx4 v[132:135], v163, s[20:21] offset:256
	v_lshlrev_b32_e32 v164, 6, v166
	v_and_b32_e32 v165, 0x30, v225
	v_add_u32_e32 v165, v164, v165
	v_lshlrev_b32_e32 v167, 12, v166
	v_lshl_add_u32 v167, v162, 2, v167
	v_lshlrev_b32_e32 v168, 2, v162
	v_xor_b32_e32 v169, 16, v225
	v_xor_b32_e32 v170, 32, v225
	v_lshlrev_b32_e32 v169, 2, v169
	v_lshlrev_b32_e32 v170, 2, v170
	s_cmpk_gt_u32 s92, 0xff
	s_cbranch_scc1 .Lf2e_nox
	s_barrier
.Lf2e_nox:
	s_waitcnt vmcnt(14)
	v_lshlrev_b32_e32 v192, 16, v200
	v_and_b32_e32 v193, 0xffff0000, v200
	v_pk_add_f32 v[148:149], v[148:149], v[192:193]
	v_lshlrev_b32_e32 v194, 16, v201
	v_and_b32_e32 v195, 0xffff0000, v201
	v_pk_add_f32 v[150:151], v[150:151], v[194:195]
	v_pk_mul_f32 v[184:185], v[148:149], v[148:149]
	v_pk_fma_f32 v[184:185], v[150:151], v[150:151], v[184:185]
	v_lshlrev_b32_e32 v192, 16, v202
	v_and_b32_e32 v193, 0xffff0000, v202
	v_pk_add_f32 v[144:145], v[144:145], v[192:193]
	v_lshlrev_b32_e32 v194, 16, v203
	v_and_b32_e32 v195, 0xffff0000, v203
	v_pk_add_f32 v[146:147], v[146:147], v[194:195]
	v_pk_fma_f32 v[184:185], v[144:145], v[144:145], v[184:185]
	v_pk_fma_f32 v[184:185], v[146:147], v[146:147], v[184:185]
	v_lshlrev_b32_e32 v192, 16, v204
	v_and_b32_e32 v193, 0xffff0000, v204
	v_pk_add_f32 v[140:141], v[140:141], v[192:193]
	v_lshlrev_b32_e32 v194, 16, v205
	v_and_b32_e32 v195, 0xffff0000, v205
	v_pk_add_f32 v[142:143], v[142:143], v[194:195]
	v_pk_fma_f32 v[184:185], v[140:141], v[140:141], v[184:185]
	v_pk_fma_f32 v[184:185], v[142:143], v[142:143], v[184:185]
	v_lshlrev_b32_e32 v192, 16, v206
	v_and_b32_e32 v193, 0xffff0000, v206
	v_pk_add_f32 v[136:137], v[136:137], v[192:193]
	v_lshlrev_b32_e32 v194, 16, v207
	v_and_b32_e32 v195, 0xffff0000, v207
	v_pk_add_f32 v[138:139], v[138:139], v[194:195]
	v_pk_fma_f32 v[184:185], v[136:137], v[136:137], v[184:185]
	v_pk_fma_f32 v[184:185], v[138:139], v[138:139], v[184:185]
	v_add_f32_e32 v200, v184, v185
	s_waitcnt vmcnt(12)
	v_lshlrev_b32_e32 v192, 16, v208
	v_and_b32_e32 v193, 0xffff0000, v208
	v_pk_add_f32 v[108:109], v[108:109], v[192:193]
	v_lshlrev_b32_e32 v194, 16, v209
	v_and_b32_e32 v195, 0xffff0000, v209
	v_pk_add_f32 v[110:111], v[110:111], v[194:195]
	v_pk_mul_f32 v[184:185], v[108:109], v[108:109]
	v_pk_fma_f32 v[184:185], v[110:111], v[110:111], v[184:185]
	v_lshlrev_b32_e32 v192, 16, v210
	v_and_b32_e32 v193, 0xffff0000, v210
	v_pk_add_f32 v[104:105], v[104:105], v[192:193]
	v_lshlrev_b32_e32 v194, 16, v211
	v_and_b32_e32 v195, 0xffff0000, v211
	v_pk_add_f32 v[106:107], v[106:107], v[194:195]
	v_pk_fma_f32 v[184:185], v[104:105], v[104:105], v[184:185]
	v_pk_fma_f32 v[184:185], v[106:107], v[106:107], v[184:185]
	v_lshlrev_b32_e32 v192, 16, v212
	v_and_b32_e32 v193, 0xffff0000, v212
	v_pk_add_f32 v[100:101], v[100:101], v[192:193]
	v_lshlrev_b32_e32 v194, 16, v213
	v_and_b32_e32 v195, 0xffff0000, v213
	v_pk_add_f32 v[102:103], v[102:103], v[194:195]
	v_pk_fma_f32 v[184:185], v[100:101], v[100:101], v[184:185]
	v_pk_fma_f32 v[184:185], v[102:103], v[102:103], v[184:185]
	v_lshlrev_b32_e32 v192, 16, v214
	v_and_b32_e32 v193, 0xffff0000, v214
	v_pk_add_f32 v[96:97], v[96:97], v[192:193]
	v_lshlrev_b32_e32 v194, 16, v215
	v_and_b32_e32 v195, 0xffff0000, v215
	v_pk_add_f32 v[98:99], v[98:99], v[194:195]
	v_pk_fma_f32 v[184:185], v[96:97], v[96:97], v[184:185]
	v_pk_fma_f32 v[184:185], v[98:99], v[98:99], v[184:185]
	v_add_f32_e32 v208, v184, v185
	s_waitcnt vmcnt(10)
	v_lshlrev_b32_e32 v192, 16, v216
	v_and_b32_e32 v193, 0xffff0000, v216
	v_pk_add_f32 v[92:93], v[92:93], v[192:193]
	v_lshlrev_b32_e32 v194, 16, v217
	v_and_b32_e32 v195, 0xffff0000, v217
	v_pk_add_f32 v[94:95], v[94:95], v[194:195]
	v_pk_mul_f32 v[184:185], v[92:93], v[92:93]
	v_pk_fma_f32 v[184:185], v[94:95], v[94:95], v[184:185]
	v_lshlrev_b32_e32 v192, 16, v218
	v_and_b32_e32 v193, 0xffff0000, v218
	v_pk_add_f32 v[88:89], v[88:89], v[192:193]
	v_lshlrev_b32_e32 v194, 16, v219
	v_and_b32_e32 v195, 0xffff0000, v219
	v_pk_add_f32 v[90:91], v[90:91], v[194:195]
	v_pk_fma_f32 v[184:185], v[88:89], v[88:89], v[184:185]
	v_pk_fma_f32 v[184:185], v[90:91], v[90:91], v[184:185]
	v_lshlrev_b32_e32 v192, 16, v232
	v_and_b32_e32 v193, 0xffff0000, v232
	v_pk_add_f32 v[84:85], v[84:85], v[192:193]
	v_lshlrev_b32_e32 v194, 16, v233
	v_and_b32_e32 v195, 0xffff0000, v233
	v_pk_add_f32 v[86:87], v[86:87], v[194:195]
	v_pk_fma_f32 v[184:185], v[84:85], v[84:85], v[184:185]
	v_pk_fma_f32 v[184:185], v[86:87], v[86:87], v[184:185]
	v_lshlrev_b32_e32 v192, 16, v234
	v_and_b32_e32 v193, 0xffff0000, v234
	v_pk_add_f32 v[80:81], v[80:81], v[192:193]
	v_lshlrev_b32_e32 v194, 16, v235
	v_and_b32_e32 v195, 0xffff0000, v235
	v_pk_add_f32 v[82:83], v[82:83], v[194:195]
	v_pk_fma_f32 v[184:185], v[80:81], v[80:81], v[184:185]
	v_pk_fma_f32 v[184:185], v[82:83], v[82:83], v[184:185]
	v_add_f32_e32 v216, v184, v185
	s_waitcnt vmcnt(8)
	v_lshlrev_b32_e32 v192, 16, v236
	v_and_b32_e32 v193, 0xffff0000, v236
	v_pk_add_f32 v[76:77], v[76:77], v[192:193]
	v_lshlrev_b32_e32 v194, 16, v237
	v_and_b32_e32 v195, 0xffff0000, v237
	v_pk_add_f32 v[78:79], v[78:79], v[194:195]
	v_pk_mul_f32 v[184:185], v[76:77], v[76:77]
	v_pk_fma_f32 v[184:185], v[78:79], v[78:79], v[184:185]
	v_lshlrev_b32_e32 v192, 16, v238
	v_and_b32_e32 v193, 0xffff0000, v238
	v_pk_add_f32 v[72:73], v[72:73], v[192:193]
	v_lshlrev_b32_e32 v194, 16, v239
	v_and_b32_e32 v195, 0xffff0000, v239
	v_pk_add_f32 v[74:75], v[74:75], v[194:195]
	v_pk_fma_f32 v[184:185], v[72:73], v[72:73], v[184:185]
	v_pk_fma_f32 v[184:185], v[74:75], v[74:75], v[184:185]
	v_lshlrev_b32_e32 v192, 16, v240
	v_and_b32_e32 v193, 0xffff0000, v240
	v_pk_add_f32 v[68:69], v[68:69], v[192:193]
	v_lshlrev_b32_e32 v194, 16, v241
	v_and_b32_e32 v195, 0xffff0000, v241
	v_pk_add_f32 v[70:71], v[70:71], v[194:195]
	v_pk_fma_f32 v[184:185], v[68:69], v[68:69], v[184:185]
	v_pk_fma_f32 v[184:185], v[70:71], v[70:71], v[184:185]
	v_lshlrev_b32_e32 v192, 16, v242
	v_and_b32_e32 v193, 0xffff0000, v242
	v_pk_add_f32 v[64:65], v[64:65], v[192:193]
	v_lshlrev_b32_e32 v194, 16, v243
	v_and_b32_e32 v195, 0xffff0000, v243
	v_pk_add_f32 v[66:67], v[66:67], v[194:195]
	v_pk_fma_f32 v[184:185], v[64:65], v[64:65], v[184:185]
	v_pk_fma_f32 v[184:185], v[66:67], v[66:67], v[184:185]
	v_add_f32_e32 v236, v184, v185
	s_waitcnt vmcnt(6)
	v_lshlrev_b32_e32 v192, 16, v244
	v_and_b32_e32 v193, 0xffff0000, v244
	v_pk_add_f32 v[60:61], v[60:61], v[192:193]
	v_lshlrev_b32_e32 v194, 16, v245
	v_and_b32_e32 v195, 0xffff0000, v245
	v_pk_add_f32 v[62:63], v[62:63], v[194:195]
	v_pk_mul_f32 v[184:185], v[60:61], v[60:61]
	v_pk_fma_f32 v[184:185], v[62:63], v[62:63], v[184:185]
	v_lshlrev_b32_e32 v192, 16, v246
	v_and_b32_e32 v193, 0xffff0000, v246
	v_pk_add_f32 v[56:57], v[56:57], v[192:193]
	v_lshlrev_b32_e32 v194, 16, v247
	v_and_b32_e32 v195, 0xffff0000, v247
	v_pk_add_f32 v[58:59], v[58:59], v[194:195]
	v_pk_fma_f32 v[184:185], v[56:57], v[56:57], v[184:185]
	v_pk_fma_f32 v[184:185], v[58:59], v[58:59], v[184:185]
	v_lshlrev_b32_e32 v192, 16, v248
	v_and_b32_e32 v193, 0xffff0000, v248
	v_pk_add_f32 v[52:53], v[52:53], v[192:193]
	v_lshlrev_b32_e32 v194, 16, v249
	v_and_b32_e32 v195, 0xffff0000, v249
	v_pk_add_f32 v[54:55], v[54:55], v[194:195]
	v_pk_fma_f32 v[184:185], v[52:53], v[52:53], v[184:185]
	v_pk_fma_f32 v[184:185], v[54:55], v[54:55], v[184:185]
	v_lshlrev_b32_e32 v192, 16, v250
	v_and_b32_e32 v193, 0xffff0000, v250
	v_pk_add_f32 v[48:49], v[48:49], v[192:193]
	v_lshlrev_b32_e32 v194, 16, v251
	v_and_b32_e32 v195, 0xffff0000, v251
	v_pk_add_f32 v[50:51], v[50:51], v[194:195]
	v_pk_fma_f32 v[184:185], v[48:49], v[48:49], v[184:185]
	v_pk_fma_f32 v[184:185], v[50:51], v[50:51], v[184:185]
	v_add_f32_e32 v244, v184, v185
	s_waitcnt vmcnt(4)
	v_lshlrev_b32_e32 v192, 16, v112
	v_and_b32_e32 v193, 0xffff0000, v112
	v_pk_add_f32 v[44:45], v[44:45], v[192:193]
	v_lshlrev_b32_e32 v194, 16, v113
	v_and_b32_e32 v195, 0xffff0000, v113
	v_pk_add_f32 v[46:47], v[46:47], v[194:195]
	v_pk_mul_f32 v[184:185], v[44:45], v[44:45]
	v_pk_fma_f32 v[184:185], v[46:47], v[46:47], v[184:185]
	v_lshlrev_b32_e32 v192, 16, v114
	v_and_b32_e32 v193, 0xffff0000, v114
	v_pk_add_f32 v[40:41], v[40:41], v[192:193]
	v_lshlrev_b32_e32 v194, 16, v115
	v_and_b32_e32 v195, 0xffff0000, v115
	v_pk_add_f32 v[42:43], v[42:43], v[194:195]
	v_pk_fma_f32 v[184:185], v[40:41], v[40:41], v[184:185]
	v_pk_fma_f32 v[184:185], v[42:43], v[42:43], v[184:185]
	v_lshlrev_b32_e32 v192, 16, v116
	v_and_b32_e32 v193, 0xffff0000, v116
	v_pk_add_f32 v[36:37], v[36:37], v[192:193]
	v_lshlrev_b32_e32 v194, 16, v117
	v_and_b32_e32 v195, 0xffff0000, v117
	v_pk_add_f32 v[38:39], v[38:39], v[194:195]
	v_pk_fma_f32 v[184:185], v[36:37], v[36:37], v[184:185]
	v_pk_fma_f32 v[184:185], v[38:39], v[38:39], v[184:185]
	v_lshlrev_b32_e32 v192, 16, v118
	v_and_b32_e32 v193, 0xffff0000, v118
	v_pk_add_f32 v[32:33], v[32:33], v[192:193]
	v_lshlrev_b32_e32 v194, 16, v119
	v_and_b32_e32 v195, 0xffff0000, v119
	v_pk_add_f32 v[34:35], v[34:35], v[194:195]
	v_pk_fma_f32 v[184:185], v[32:33], v[32:33], v[184:185]
	v_pk_fma_f32 v[184:185], v[34:35], v[34:35], v[184:185]
	v_add_f32_e32 v112, v184, v185
	s_waitcnt vmcnt(2)
	v_lshlrev_b32_e32 v192, 16, v120
	v_and_b32_e32 v193, 0xffff0000, v120
	v_pk_add_f32 v[28:29], v[28:29], v[192:193]
	v_lshlrev_b32_e32 v194, 16, v121
	v_and_b32_e32 v195, 0xffff0000, v121
	v_pk_add_f32 v[30:31], v[30:31], v[194:195]
	v_pk_mul_f32 v[184:185], v[28:29], v[28:29]
	v_pk_fma_f32 v[184:185], v[30:31], v[30:31], v[184:185]
	v_lshlrev_b32_e32 v192, 16, v122
	v_and_b32_e32 v193, 0xffff0000, v122
	v_pk_add_f32 v[24:25], v[24:25], v[192:193]
	v_lshlrev_b32_e32 v194, 16, v123
	v_and_b32_e32 v195, 0xffff0000, v123
	v_pk_add_f32 v[26:27], v[26:27], v[194:195]
	v_pk_fma_f32 v[184:185], v[24:25], v[24:25], v[184:185]
	v_pk_fma_f32 v[184:185], v[26:27], v[26:27], v[184:185]
	v_lshlrev_b32_e32 v192, 16, v124
	v_and_b32_e32 v193, 0xffff0000, v124
	v_pk_add_f32 v[20:21], v[20:21], v[192:193]
	v_lshlrev_b32_e32 v194, 16, v125
	v_and_b32_e32 v195, 0xffff0000, v125
	v_pk_add_f32 v[22:23], v[22:23], v[194:195]
	v_pk_fma_f32 v[184:185], v[20:21], v[20:21], v[184:185]
	v_pk_fma_f32 v[184:185], v[22:23], v[22:23], v[184:185]
	v_lshlrev_b32_e32 v192, 16, v126
	v_and_b32_e32 v193, 0xffff0000, v126
	v_pk_add_f32 v[16:17], v[16:17], v[192:193]
	v_lshlrev_b32_e32 v194, 16, v127
	v_and_b32_e32 v195, 0xffff0000, v127
	v_pk_add_f32 v[18:19], v[18:19], v[194:195]
	v_pk_fma_f32 v[184:185], v[16:17], v[16:17], v[184:185]
	v_pk_fma_f32 v[184:185], v[18:19], v[18:19], v[184:185]
	v_add_f32_e32 v120, v184, v185
	s_waitcnt vmcnt(0)
	v_lshlrev_b32_e32 v192, 16, v128
	v_and_b32_e32 v193, 0xffff0000, v128
	v_pk_add_f32 v[12:13], v[12:13], v[192:193]
	v_lshlrev_b32_e32 v194, 16, v129
	v_and_b32_e32 v195, 0xffff0000, v129
	v_pk_add_f32 v[14:15], v[14:15], v[194:195]
	v_pk_mul_f32 v[184:185], v[12:13], v[12:13]
	v_pk_fma_f32 v[184:185], v[14:15], v[14:15], v[184:185]
	v_lshlrev_b32_e32 v192, 16, v130
	v_and_b32_e32 v193, 0xffff0000, v130
	v_pk_add_f32 v[8:9], v[8:9], v[192:193]
	v_lshlrev_b32_e32 v194, 16, v131
	v_and_b32_e32 v195, 0xffff0000, v131
	v_pk_add_f32 v[10:11], v[10:11], v[194:195]
	v_pk_fma_f32 v[184:185], v[8:9], v[8:9], v[184:185]
	v_pk_fma_f32 v[184:185], v[10:11], v[10:11], v[184:185]
	v_lshlrev_b32_e32 v192, 16, v132
	v_and_b32_e32 v193, 0xffff0000, v132
	v_pk_add_f32 v[4:5], v[4:5], v[192:193]
	v_lshlrev_b32_e32 v194, 16, v133
	v_and_b32_e32 v195, 0xffff0000, v133
	v_pk_add_f32 v[6:7], v[6:7], v[194:195]
	v_pk_fma_f32 v[184:185], v[4:5], v[4:5], v[184:185]
	v_pk_fma_f32 v[184:185], v[6:7], v[6:7], v[184:185]
	v_lshlrev_b32_e32 v192, 16, v134
	v_and_b32_e32 v193, 0xffff0000, v134
	v_pk_add_f32 v[0:1], v[0:1], v[192:193]
	v_lshlrev_b32_e32 v194, 16, v135
	v_and_b32_e32 v195, 0xffff0000, v135
	v_pk_add_f32 v[2:3], v[2:3], v[194:195]
	v_pk_fma_f32 v[184:185], v[0:1], v[0:1], v[184:185]
	v_pk_fma_f32 v[184:185], v[2:3], v[2:3], v[184:185]
	v_add_f32_e32 v128, v184, v185
	ds_bpermute_b32 v201, v169, v200
	ds_bpermute_b32 v209, v169, v208
	ds_bpermute_b32 v217, v169, v216
	ds_bpermute_b32 v237, v169, v236
	ds_bpermute_b32 v245, v169, v244
	ds_bpermute_b32 v113, v169, v112
	ds_bpermute_b32 v121, v169, v120
	ds_bpermute_b32 v129, v169, v128
	s_lshl_b32 s28, s34, 4
	s_lshl_b32 s29, s9, 2
	s_add_i32 s28, s28, s29
	s_add_u32 s20, s62, s28
	s_addc_u32 s21, s63, 0
	s_add_u32 s72, s20, 0x2000
	s_addc_u32 s73, s21, 0
	s_waitcnt lgkmcnt(0)
	v_add_f32_e32 v200, v200, v201
	v_add_f32_e32 v208, v208, v209
	v_add_f32_e32 v216, v216, v217
	v_add_f32_e32 v236, v236, v237
	v_add_f32_e32 v244, v244, v245
	v_add_f32_e32 v112, v112, v113
	v_add_f32_e32 v120, v120, v121
	v_add_f32_e32 v128, v128, v129
	ds_bpermute_b32 v201, v170, v200
	ds_bpermute_b32 v209, v170, v208
	ds_bpermute_b32 v217, v170, v216
	ds_bpermute_b32 v237, v170, v236
	ds_bpermute_b32 v245, v170, v244
	ds_bpermute_b32 v113, v170, v112
	ds_bpermute_b32 v121, v170, v120
	ds_bpermute_b32 v129, v170, v128
	s_mul_i32 s28, s2, 0xaaab
	s_lshr_b32 s28, s28, 17
	s_mul_i32 s29, s28, 3
	s_sub_i32 s29, s2, s29
	s_add_i32 s29, s29, 1
	s_lshl_b32 s29, s29, 6
	s_lshl_b32 s28, s28, 8
	s_add_i32 s28, s28, s29
	s_add_u32 s28, s28, 0x1f600400
	s_add_u32 s94, s64, s28
	s_addc_u32 s95, s65, 0
	s_waitcnt lgkmcnt(0)
	v_add_f32_e32 v200, v200, v201
	v_add_f32_e32 v208, v208, v209
	v_add_f32_e32 v216, v216, v217
	v_add_f32_e32 v236, v236, v237
	v_add_f32_e32 v244, v244, v245
	v_add_f32_e32 v112, v112, v113
	v_add_f32_e32 v120, v120, v121
	v_add_f32_e32 v128, v128, v129
	s_mov_b64 exec, s[38:39]
	global_store_dword v164, v200, s[20:21] offset:0 sc1
	global_store_dword v164, v208, s[20:21] offset:1024 sc1
	global_store_dword v164, v216, s[20:21] offset:2048 sc1
	global_store_dword v164, v236, s[20:21] offset:3072 sc1
	global_store_dword v164, v244, s[72:73] offset:0 sc1
	global_store_dword v164, v112, s[72:73] offset:1024 sc1
	global_store_dword v164, v120, s[72:73] offset:2048 sc1
	global_store_dword v164, v128, s[72:73] offset:3072 sc1
	s_mov_b64 exec, -1
	s_lshr_b32 s50, s92, 8
	s_lshl_b32 s50, s50, 4
	s_lshl_b32 s29, 1, s50
	v_mov_b32_e32 v171, s29
	s_waitcnt vmcnt(0)
	s_mov_b64 exec, 1
	global_atomic_add v177, v171, s[94:95]
	s_mov_b64 exec, -1
	global_load_dwordx4 v[120:123], v168, s[48:49]
	global_load_dwordx4 v[124:127], v168, s[48:49] offset:16
	global_load_dwordx4 v[128:131], v168, s[48:49] offset:512
	global_load_dwordx4 v[132:135], v168, s[48:49] offset:528
	s_mov_b32 s29, 0
.Lf2e_poll:
	global_load_dword v171, v177, s[94:95] sc1
	s_waitcnt vmcnt(0)
	v_readfirstlane_b32 s28, v171
	s_lshr_b32 s28, s28, s50
	s_and_b32 s28, s28, 0xffff
	s_cmp_ge_u32 s28, 16
	s_cbranch_scc1 .Lf2e_ready
	s_sleep 2
	s_add_i32 s29, s29, 1
	s_cmp_lt_u32 s29, 0x4000
	s_cbranch_scc1 .Lf2e_poll
.Lf2e_ready:
	s_add_u32 s72, s62, 0x2000
	s_addc_u32 s73, s63, 0
	global_load_dwordx4 v[200:203], v165, s[62:63] offset:0 sc1
	global_load_dwordx4 v[204:207], v165, s[62:63] offset:1024 sc1
	global_load_dwordx4 v[208:211], v165, s[62:63] offset:2048 sc1
	global_load_dwordx4 v[212:215], v165, s[62:63] offset:3072 sc1
	global_load_dwordx4 v[216:219], v165, s[72:73] offset:0 sc1
	global_load_dwordx4 v[232:235], v165, s[72:73] offset:1024 sc1
	global_load_dwordx4 v[236:239], v165, s[72:73] offset:2048 sc1
	global_load_dwordx4 v[240:243], v165, s[72:73] offset:3072 sc1
	s_waitcnt vmcnt(0)
	v_add_f32_e32 v200, v200, v201
	v_add_f32_e32 v202, v202, v203
	v_add_f32_e32 v204, v204, v205
	v_add_f32_e32 v206, v206, v207
	v_add_f32_e32 v208, v208, v209
	v_add_f32_e32 v210, v210, v211
	v_add_f32_e32 v212, v212, v213
	v_add_f32_e32 v214, v214, v215
	v_add_f32_e32 v216, v216, v217
	v_add_f32_e32 v218, v218, v219
	v_add_f32_e32 v232, v232, v233
	v_add_f32_e32 v234, v234, v235
	v_add_f32_e32 v236, v236, v237
	v_add_f32_e32 v238, v238, v239
	v_add_f32_e32 v240, v240, v241
	v_add_f32_e32 v242, v242, v243
	v_add_f32_e32 v200, v200, v202
	v_add_f32_e32 v204, v204, v206
	v_add_f32_e32 v208, v208, v210
	v_add_f32_e32 v212, v212, v214
	v_add_f32_e32 v216, v216, v218
	v_add_f32_e32 v232, v232, v234
	v_add_f32_e32 v236, v236, v238
	v_add_f32_e32 v240, v240, v242
	ds_bpermute_b32 v201, v169, v200
	ds_bpermute_b32 v205, v169, v204
	ds_bpermute_b32 v209, v169, v208
	ds_bpermute_b32 v213, v169, v212
	ds_bpermute_b32 v217, v169, v216
	ds_bpermute_b32 v233, v169, v232
	ds_bpermute_b32 v237, v169, v236
	ds_bpermute_b32 v241, v169, v240
	s_waitcnt lgkmcnt(0)
	v_add_f32_e32 v200, v200, v201
	v_add_f32_e32 v204, v204, v205
	v_add_f32_e32 v208, v208, v209
	v_add_f32_e32 v212, v212, v213
	v_add_f32_e32 v216, v216, v217
	v_add_f32_e32 v232, v232, v233
	v_add_f32_e32 v236, v236, v237
	v_add_f32_e32 v240, v240, v241
	ds_bpermute_b32 v201, v170, v200
	ds_bpermute_b32 v205, v170, v204
	ds_bpermute_b32 v209, v170, v208
	ds_bpermute_b32 v213, v170, v212
	ds_bpermute_b32 v217, v170, v216
	ds_bpermute_b32 v233, v170, v232
	ds_bpermute_b32 v237, v170, v236
	ds_bpermute_b32 v241, v170, v240
	s_waitcnt lgkmcnt(0)
	v_add_f32_e32 v200, v200, v201
	v_add_f32_e32 v204, v204, v205
	v_add_f32_e32 v208, v208, v209
	v_add_f32_e32 v212, v212, v213
	v_add_f32_e32 v216, v216, v217
	v_add_f32_e32 v232, v232, v233
	v_add_f32_e32 v236, v236, v237
	v_add_f32_e32 v240, v240, v241
	v_mul_f32_e32 v200, 0x3a800000, v200
	v_mul_f32_e32 v204, 0x3a800000, v204
	v_mul_f32_e32 v208, 0x3a800000, v208
	v_mul_f32_e32 v212, 0x3a800000, v212
	v_mul_f32_e32 v216, 0x3a800000, v216
	v_mul_f32_e32 v232, 0x3a800000, v232
	v_mul_f32_e32 v236, 0x3a800000, v236
	v_mul_f32_e32 v240, 0x3a800000, v240
	v_add_f32_e32 v200, 0x3727c5ac, v200
	v_add_f32_e32 v204, 0x3727c5ac, v204
	v_add_f32_e32 v208, 0x3727c5ac, v208
	v_add_f32_e32 v212, 0x3727c5ac, v212
	v_add_f32_e32 v216, 0x3727c5ac, v216
	v_add_f32_e32 v232, 0x3727c5ac, v232
	v_add_f32_e32 v236, 0x3727c5ac, v236
	v_add_f32_e32 v240, 0x3727c5ac, v240
	v_rsq_f32_e32 v200, v200
	v_rsq_f32_e32 v204, v204
	v_rsq_f32_e32 v208, v208
	v_rsq_f32_e32 v212, v212
	v_rsq_f32_e32 v216, v216
	v_rsq_f32_e32 v232, v232
	v_rsq_f32_e32 v236, v236
	v_rsq_f32_e32 v240, v240
	v_pk_mul_f32 v[148:149], v[200:201], v[148:149] op_sel_hi:[0,1]
	v_pk_mul_f32 v[150:151], v[200:201], v[150:151] op_sel_hi:[0,1]
	v_pk_mul_f32 v[148:149], v[120:121], v[148:149]
	v_pk_mul_f32 v[150:151], v[122:123], v[150:151]
	global_store_dwordx4 v167, v[148:151], s[60:61]
	v_pk_mul_f32 v[144:145], v[200:201], v[144:145] op_sel_hi:[0,1]
	v_pk_mul_f32 v[146:147], v[200:201], v[146:147] op_sel_hi:[0,1]
	v_pk_mul_f32 v[144:145], v[124:125], v[144:145]
	v_pk_mul_f32 v[146:147], v[126:127], v[146:147]
	global_store_dwordx4 v167, v[144:147], s[60:61] offset:16
	v_pk_mul_f32 v[140:141], v[200:201], v[140:141] op_sel_hi:[0,1]
	v_pk_mul_f32 v[142:143], v[200:201], v[142:143] op_sel_hi:[0,1]
	v_pk_mul_f32 v[140:141], v[128:129], v[140:141]
	v_pk_mul_f32 v[142:143], v[130:131], v[142:143]
	global_store_dwordx4 v167, v[140:143], s[60:61] offset:512
	v_pk_mul_f32 v[136:137], v[200:201], v[136:137] op_sel_hi:[0,1]
	v_pk_mul_f32 v[138:139], v[200:201], v[138:139] op_sel_hi:[0,1]
	v_pk_mul_f32 v[136:137], v[132:133], v[136:137]
	v_pk_mul_f32 v[138:139], v[134:135], v[138:139]
	global_store_dwordx4 v167, v[136:139], s[60:61] offset:528
	s_add_u32 s28, s60, 0x10000
	s_addc_u32 s29, s61, 0
	v_pk_mul_f32 v[108:109], v[204:205], v[108:109] op_sel_hi:[0,1]
	v_pk_mul_f32 v[110:111], v[204:205], v[110:111] op_sel_hi:[0,1]
	v_pk_mul_f32 v[108:109], v[120:121], v[108:109]
	v_pk_mul_f32 v[110:111], v[122:123], v[110:111]
	global_store_dwordx4 v167, v[108:111], s[28:29]
	v_pk_mul_f32 v[104:105], v[204:205], v[104:105] op_sel_hi:[0,1]
	v_pk_mul_f32 v[106:107], v[204:205], v[106:107] op_sel_hi:[0,1]
	v_pk_mul_f32 v[104:105], v[124:125], v[104:105]
	v_pk_mul_f32 v[106:107], v[126:127], v[106:107]
	global_store_dwordx4 v167, v[104:107], s[28:29] offset:16
	v_pk_mul_f32 v[100:101], v[204:205], v[100:101] op_sel_hi:[0,1]
	v_pk_mul_f32 v[102:103], v[204:205], v[102:103] op_sel_hi:[0,1]
	v_pk_mul_f32 v[100:101], v[128:129], v[100:101]
	v_pk_mul_f32 v[102:103], v[130:131], v[102:103]
	global_store_dwordx4 v167, v[100:103], s[28:29] offset:512
	v_pk_mul_f32 v[96:97], v[204:205], v[96:97] op_sel_hi:[0,1]
	v_pk_mul_f32 v[98:99], v[204:205], v[98:99] op_sel_hi:[0,1]
	v_pk_mul_f32 v[96:97], v[132:133], v[96:97]
	v_pk_mul_f32 v[98:99], v[134:135], v[98:99]
	global_store_dwordx4 v167, v[96:99], s[28:29] offset:528
	s_add_u32 s28, s60, 0x20000
	s_addc_u32 s29, s61, 0
	v_pk_mul_f32 v[92:93], v[208:209], v[92:93] op_sel_hi:[0,1]
	v_pk_mul_f32 v[94:95], v[208:209], v[94:95] op_sel_hi:[0,1]
	v_pk_mul_f32 v[92:93], v[120:121], v[92:93]
	v_pk_mul_f32 v[94:95], v[122:123], v[94:95]
	global_store_dwordx4 v167, v[92:95], s[28:29]
	v_pk_mul_f32 v[88:89], v[208:209], v[88:89] op_sel_hi:[0,1]
	v_pk_mul_f32 v[90:91], v[208:209], v[90:91] op_sel_hi:[0,1]
	v_pk_mul_f32 v[88:89], v[124:125], v[88:89]
	v_pk_mul_f32 v[90:91], v[126:127], v[90:91]
	global_store_dwordx4 v167, v[88:91], s[28:29] offset:16
	v_pk_mul_f32 v[84:85], v[208:209], v[84:85] op_sel_hi:[0,1]
	v_pk_mul_f32 v[86:87], v[208:209], v[86:87] op_sel_hi:[0,1]
	v_pk_mul_f32 v[84:85], v[128:129], v[84:85]
	v_pk_mul_f32 v[86:87], v[130:131], v[86:87]
	global_store_dwordx4 v167, v[84:87], s[28:29] offset:512
	v_pk_mul_f32 v[80:81], v[208:209], v[80:81] op_sel_hi:[0,1]
	v_pk_mul_f32 v[82:83], v[208:209], v[82:83] op_sel_hi:[0,1]
	v_pk_mul_f32 v[80:81], v[132:133], v[80:81]
	v_pk_mul_f32 v[82:83], v[134:135], v[82:83]
	global_store_dwordx4 v167, v[80:83], s[28:29] offset:528
	s_add_u32 s28, s60, 0x30000
	s_addc_u32 s29, s61, 0
	v_pk_mul_f32 v[76:77], v[212:213], v[76:77] op_sel_hi:[0,1]
	v_pk_mul_f32 v[78:79], v[212:213], v[78:79] op_sel_hi:[0,1]
	v_pk_mul_f32 v[76:77], v[120:121], v[76:77]
	v_pk_mul_f32 v[78:79], v[122:123], v[78:79]
	global_store_dwordx4 v167, v[76:79], s[28:29]
	v_pk_mul_f32 v[72:73], v[212:213], v[72:73] op_sel_hi:[0,1]
	v_pk_mul_f32 v[74:75], v[212:213], v[74:75] op_sel_hi:[0,1]
	v_pk_mul_f32 v[72:73], v[124:125], v[72:73]
	v_pk_mul_f32 v[74:75], v[126:127], v[74:75]
	global_store_dwordx4 v167, v[72:75], s[28:29] offset:16
	v_pk_mul_f32 v[68:69], v[212:213], v[68:69] op_sel_hi:[0,1]
	v_pk_mul_f32 v[70:71], v[212:213], v[70:71] op_sel_hi:[0,1]
	v_pk_mul_f32 v[68:69], v[128:129], v[68:69]
	v_pk_mul_f32 v[70:71], v[130:131], v[70:71]
	global_store_dwordx4 v167, v[68:71], s[28:29] offset:512
	v_pk_mul_f32 v[64:65], v[212:213], v[64:65] op_sel_hi:[0,1]
	v_pk_mul_f32 v[66:67], v[212:213], v[66:67] op_sel_hi:[0,1]
	v_pk_mul_f32 v[64:65], v[132:133], v[64:65]
	v_pk_mul_f32 v[66:67], v[134:135], v[66:67]
	global_store_dwordx4 v167, v[64:67], s[28:29] offset:528
	s_add_u32 s28, s60, 0x80000
	s_addc_u32 s29, s61, 0
	v_pk_mul_f32 v[60:61], v[216:217], v[60:61] op_sel_hi:[0,1]
	v_pk_mul_f32 v[62:63], v[216:217], v[62:63] op_sel_hi:[0,1]
	v_pk_mul_f32 v[60:61], v[120:121], v[60:61]
	v_pk_mul_f32 v[62:63], v[122:123], v[62:63]
	global_store_dwordx4 v167, v[60:63], s[28:29]
	v_pk_mul_f32 v[56:57], v[216:217], v[56:57] op_sel_hi:[0,1]
	v_pk_mul_f32 v[58:59], v[216:217], v[58:59] op_sel_hi:[0,1]
	v_pk_mul_f32 v[56:57], v[124:125], v[56:57]
	v_pk_mul_f32 v[58:59], v[126:127], v[58:59]
	global_store_dwordx4 v167, v[56:59], s[28:29] offset:16
	v_pk_mul_f32 v[52:53], v[216:217], v[52:53] op_sel_hi:[0,1]
	v_pk_mul_f32 v[54:55], v[216:217], v[54:55] op_sel_hi:[0,1]
	v_pk_mul_f32 v[52:53], v[128:129], v[52:53]
	v_pk_mul_f32 v[54:55], v[130:131], v[54:55]
	global_store_dwordx4 v167, v[52:55], s[28:29] offset:512
	v_pk_mul_f32 v[48:49], v[216:217], v[48:49] op_sel_hi:[0,1]
	v_pk_mul_f32 v[50:51], v[216:217], v[50:51] op_sel_hi:[0,1]
	v_pk_mul_f32 v[48:49], v[132:133], v[48:49]
	v_pk_mul_f32 v[50:51], v[134:135], v[50:51]
	global_store_dwordx4 v167, v[48:51], s[28:29] offset:528
	s_add_u32 s28, s60, 0x90000
	s_addc_u32 s29, s61, 0
	v_pk_mul_f32 v[44:45], v[232:233], v[44:45] op_sel_hi:[0,1]
	v_pk_mul_f32 v[46:47], v[232:233], v[46:47] op_sel_hi:[0,1]
	v_pk_mul_f32 v[44:45], v[120:121], v[44:45]
	v_pk_mul_f32 v[46:47], v[122:123], v[46:47]
	global_store_dwordx4 v167, v[44:47], s[28:29]
	v_pk_mul_f32 v[40:41], v[232:233], v[40:41] op_sel_hi:[0,1]
	v_pk_mul_f32 v[42:43], v[232:233], v[42:43] op_sel_hi:[0,1]
	v_pk_mul_f32 v[40:41], v[124:125], v[40:41]
	v_pk_mul_f32 v[42:43], v[126:127], v[42:43]
	global_store_dwordx4 v167, v[40:43], s[28:29] offset:16
	v_pk_mul_f32 v[36:37], v[232:233], v[36:37] op_sel_hi:[0,1]
	v_pk_mul_f32 v[38:39], v[232:233], v[38:39] op_sel_hi:[0,1]
	v_pk_mul_f32 v[36:37], v[128:129], v[36:37]
	v_pk_mul_f32 v[38:39], v[130:131], v[38:39]
	global_store_dwordx4 v167, v[36:39], s[28:29] offset:512
	v_pk_mul_f32 v[32:33], v[232:233], v[32:33] op_sel_hi:[0,1]
	v_pk_mul_f32 v[34:35], v[232:233], v[34:35] op_sel_hi:[0,1]
	v_pk_mul_f32 v[32:33], v[132:133], v[32:33]
	v_pk_mul_f32 v[34:35], v[134:135], v[34:35]
	global_store_dwordx4 v167, v[32:35], s[28:29] offset:528
	s_add_u32 s28, s60, 0xa0000
	s_addc_u32 s29, s61, 0
	v_pk_mul_f32 v[28:29], v[236:237], v[28:29] op_sel_hi:[0,1]
	v_pk_mul_f32 v[30:31], v[236:237], v[30:31] op_sel_hi:[0,1]
	v_pk_mul_f32 v[28:29], v[120:121], v[28:29]
	v_pk_mul_f32 v[30:31], v[122:123], v[30:31]
	global_store_dwordx4 v167, v[28:31], s[28:29]
	v_pk_mul_f32 v[24:25], v[236:237], v[24:25] op_sel_hi:[0,1]
	v_pk_mul_f32 v[26:27], v[236:237], v[26:27] op_sel_hi:[0,1]
	v_pk_mul_f32 v[24:25], v[124:125], v[24:25]
	v_pk_mul_f32 v[26:27], v[126:127], v[26:27]
	global_store_dwordx4 v167, v[24:27], s[28:29] offset:16
	v_pk_mul_f32 v[20:21], v[236:237], v[20:21] op_sel_hi:[0,1]
	v_pk_mul_f32 v[22:23], v[236:237], v[22:23] op_sel_hi:[0,1]
	v_pk_mul_f32 v[20:21], v[128:129], v[20:21]
	v_pk_mul_f32 v[22:23], v[130:131], v[22:23]
	global_store_dwordx4 v167, v[20:23], s[28:29] offset:512
	v_pk_mul_f32 v[16:17], v[236:237], v[16:17] op_sel_hi:[0,1]
	v_pk_mul_f32 v[18:19], v[236:237], v[18:19] op_sel_hi:[0,1]
	v_pk_mul_f32 v[16:17], v[132:133], v[16:17]
	v_pk_mul_f32 v[18:19], v[134:135], v[18:19]
	global_store_dwordx4 v167, v[16:19], s[28:29] offset:528
	s_add_u32 s28, s60, 0xb0000
	s_addc_u32 s29, s61, 0
	v_pk_mul_f32 v[12:13], v[240:241], v[12:13] op_sel_hi:[0,1]
	v_pk_mul_f32 v[14:15], v[240:241], v[14:15] op_sel_hi:[0,1]
	v_pk_mul_f32 v[12:13], v[120:121], v[12:13]
	v_pk_mul_f32 v[14:15], v[122:123], v[14:15]
	global_store_dwordx4 v167, v[12:15], s[28:29]
	v_pk_mul_f32 v[8:9], v[240:241], v[8:9] op_sel_hi:[0,1]
	v_pk_mul_f32 v[10:11], v[240:241], v[10:11] op_sel_hi:[0,1]
	v_pk_mul_f32 v[8:9], v[124:125], v[8:9]
	v_pk_mul_f32 v[10:11], v[126:127], v[10:11]
	global_store_dwordx4 v167, v[8:11], s[28:29] offset:16
	v_pk_mul_f32 v[4:5], v[240:241], v[4:5] op_sel_hi:[0,1]
	v_pk_mul_f32 v[6:7], v[240:241], v[6:7] op_sel_hi:[0,1]
	v_pk_mul_f32 v[4:5], v[128:129], v[4:5]
	v_pk_mul_f32 v[6:7], v[130:131], v[6:7]
	global_store_dwordx4 v167, v[4:7], s[28:29] offset:512
	v_pk_mul_f32 v[0:1], v[240:241], v[0:1] op_sel_hi:[0,1]
	v_pk_mul_f32 v[2:3], v[240:241], v[2:3] op_sel_hi:[0,1]
	v_pk_mul_f32 v[0:1], v[132:133], v[0:1]
	v_pk_mul_f32 v[2:3], v[134:135], v[2:3]
	global_store_dwordx4 v167, v[0:3], s[28:29] offset:528
	s_mov_b64 s[28:29], -1
	s_branch .LBB0_92
.LBB0_117:
	s_waitcnt vmcnt(0)
.LBB0_119:
	s_barrier
